# peel first K-tile also for G2/G3a/G3b K-loops (header-style): C=0 first-touch MFMAs, zeroing removed; only the Y loop keeps v_pk_mov zeroing
# speedup vs baseline: 1.0074x; 1.0006x over previous
;     __host__ __device__ bool unit(int L, Unit& u) const { return order_mn(L, RT / 256, 32, u); }
;     __host__ __device__ const char* a_base(const Unit& u, int) const { return ((u.pn < 16 || u.pm >= 128) ? HX : HXV) + (size_t)u.pm * 256 * 128; }
;     __host__ __device__ bool unit(int L, Unit& u) const { if (L >= NCHB / 256) return false; u.g = g; u.pm = 0; u.pn = b * (NCHB / 256) + L; u.ks = 0; return true; }
;     __host__ __device__ bool unit(int L, Unit& u) const { constexpr int nN = TP / 256, nM = NCHB / 256; if (L >= nN * nM) return false; u.g = g; u.pm = b * nM + L / nN; u.pn = L % nN; u.ks = 0; return true; }
;     __host__ __device__ bool unit(int L, Unit& u) const { return order_mn(L, RL / 256, 8, u); }
;     __host__ __device__ bool unit(int L, Unit& u) const { return order_mn(L, RL / 256, 4, u); }
; template <class P>
; __device__ __forceinline__ void gemm_phase(LAS unsigned char* lds, const P& p, const int G, const int c) {
;     ...
;         const bool has_next = p.unit((ui + 1) * G + c, nxt);
;         const int nt = p.nt(cur);
;         const char* nA0 = has_next ? p.a_base(nxt, 0) - p.a_bias(0) : cA0; const char* nA1 = has_next ? p.a_base(nxt, S1) - p.a_bias(S1) : cA1;
;         const char* nB0 = has_next ? p.b_base(nxt, 0) - p.b_bias(0) : cB0; const char* nB1 = has_next ? p.b_base(nxt, S1) - p.b_bias(S1) : cB1;
;         for (int t = 0; t < nt; t += 2) {
;             const bool last = (t == nt - 2);
;             const bool sg1 = (NS > 1) && (t + 1 >= nt0);
;             const bool sg2 = (NS > 1) && !last && (t + 2 >= nt0);
;             const char* a1 = sg1 ? cA1 + (long)(t + 1 - nt0) * ksA1 : cA0 + (long)(t + 1) * ksA0;
;             const char* a2 = last ? nA0 : (sg2 ? cA1 + (long)(t + 2 - nt0) * ksA1 : cA0 + (long)(t + 2) * ksA0);
;             const char* b2 = last ? nB0 : (sg2 ? cB1 + (long)(t + 2 - nt0) * ksB1 : cB0 + (long)(t + 2) * ksB0);
.LBB0_276:
	s_cmpk_lt_i32 s8, 0x80
	s_cselect_b64 s[74:75], -1, 0
	s_cmpk_gt_i32 s8, 0x7f
	s_cselect_b32 s5, 4, 32
	s_ashr_i32 s61, s60, 31
	s_lshl_b64 s[18:19], s[60:61], 15
	s_lshl_b64 s[28:29], s[54:55], 19
	s_add_u32 s7, s24, s18
	s_addc_u32 s18, s25, s19
	s_add_u32 s82, s7, s28
	s_addc_u32 s83, s18, s29
	s_and_b64 s[18:19], exec, s[62:63]
	s_cselect_b32 s7, s83, s77
	s_cselect_b32 s18, s82, s76
	s_add_u32 s19, s76, 0x40000
	s_mul_i32 s28, s5, 0x410000
	s_addc_u32 s49, s77, 0
	v_lshl_add_u64 v[130:131], s[72:73], 0, v[172:173]
	s_add_i32 s55, s28, 0xff7e0000
	s_mov_b32 s57, 0
	s_mov_b64 s[76:77], 0
	s_cmp_eq_u32 s55, s76
	s_cselect_b64 s[30:31], -1, 0
	s_and_b64 vcc, exec, s[30:31]
	s_mov_b64 s[28:29], s[80:81]
	s_cbranch_vccnz .Lpeel_277
	s_add_u32 s28, s72, s76
	s_addc_u32 s29, s73, s77
	s_add_u32 s28, s28, 0x820000
	s_addc_u32 s29, s29, 0
; #define G8_STA(bufoff, ptr, sg, h) G8_STAGE1(bufoff, (ptr) + (h) * ((sg) ? hA1 : hA0), ((sg) ? voffA1 : voffA0), ((sg) ? r64A1 : r64A0))
; #define G8_STB(bufoff, ptr, sg, h) G8_STAGE1(bufoff, (ptr) + (h) * ((sg) ? hB1 : hB0), ((sg) ? voffB1 : voffB0), ((sg) ? r64B1 : r64B0))
; #define G8_LDA(dst, b, h) do { _Pragma("unroll") for (int m = 0; m < 4; ++m) _Pragma("unroll") for (int k = 0; k < 2; ++k) dst[m][k] = *(const LAS bf16x8*)(lds + G8_SA(b, h) + aoff + m * 2048 + k * 1024); } while (0)
; #define G8_LDB(dst, b, h) do { _Pragma("unroll") for (int n = 0; n < 2; ++n) _Pragma("unroll") for (int k = 0; k < 2; ++k) dst[n][k] = *(const LAS bf16x8*)(lds + G8_SB(b, h) + boff + n * 2048 + k * 1024); } while (0)
; #define G8_MMA(ai, bj, At, Bt) do { __builtin_amdgcn_s_setprio(1); _Pragma("unroll") for (int m = 0; m < 4; ++m) _Pragma("unroll") for (int n = 0; n < 2; ++n) _Pragma("unroll") for (int k = 0; k < 2; ++k) \
;         acc[ai][bj][m][n] = __builtin_amdgcn_mfma_f32_16x16x32_bf16(Bt[n][k], At[m][k], acc[ai][bj][m][n], 0, 0, 0); __builtin_amdgcn_s_setprio(0); } while (0)
; #define G8_WAIT_V(n) asm volatile("s_waitcnt vmcnt(" #n ")" ::: "memory")
; #define G8_WAIT_L(n) asm volatile("s_waitcnt lgkmcnt(" #n ")" ::: "memory")
; #define G8_BAR __builtin_amdgcn_s_barrier()
; #define G8_SCHED __builtin_amdgcn_sched_barrier(0)
; template <class P>
; __device__ __forceinline__ void gemm_phase(LAS unsigned char* lds, const P& p, const int G, const int c) {
;     ...
;             G8_LDB(B0, 0, 0); G8_LDB(B1, 0, 1); G8_SCHED; G8_LDA(At, 0, 0); G8_STA(G8_SA(1, 1), a1, sg1, 1);
;             G8_WAIT_V(8); G8_WAIT_L(0); G8_BAR; G8_MMA(0, 0, At, B0); G8_MMA(0, 1, At, B1); G8_BAR; G8_SCHED;
;             G8_LDA(At, 0, 1); G8_STB(G8_SB(0, 0), b2, sg2, 0); G8_STB(G8_SB(0, 1), b2, sg2, 1); G8_STA(G8_SA(0, 0), a2, sg2, 0);
;             G8_WAIT_V(8); G8_WAIT_L(0); G8_BAR; G8_MMA(1, 0, At, B0); G8_MMA(1, 1, At, B1); G8_BAR; G8_SCHED;
.Lpeel_277:
	v_add_u32_e32 v144, s52, v1
	ds_read_b128 v[132:135], v144
	ds_read_b128 v[136:139], v144 offset:1024
	ds_read_b128 v[140:143], v144 offset:2048
	ds_read_b128 v[176:179], v144 offset:3072
	v_add_u32_e32 v144, s53, v1
	ds_read_b128 v[180:183], v144
	ds_read_b128 v[184:187], v144 offset:1024
	ds_read_b128 v[188:191], v144 offset:2048
	ds_read_b128 v[192:195], v144 offset:3072
	s_add_i32 s57, s57, 2
	s_and_b64 s[30:31], exec, s[30:31]
	s_cselect_b32 s31, s7, s49
	s_cselect_b32 s30, s18, s19
	v_lshl_add_u64 v[144:145], v[130:131], 0, s[76:77]
	s_mov_b64 s[64:65], 0x414000
	v_lshl_add_u64 v[230:231], v[144:145], 0, s[64:65]
	s_add_i32 m0, s27, 0xc000
	s_mov_b64 s[64:65], 0x416000
	ds_read_b128 v[196:199], v175
	ds_read_b128 v[200:203], v175 offset:1024
	ds_read_b128 v[204:207], v175 offset:2048
	ds_read_b128 v[210:213], v175 offset:3072
	ds_read_b128 v[214:217], v175 offset:4096
	ds_read_b128 v[218:221], v175 offset:5120
	ds_read_b128 v[222:225], v175 offset:6144
	ds_read_b128 v[226:229], v175 offset:7168
	global_load_lds_dwordx4 v[230:231], off
	v_lshl_add_u64 v[144:145], v[144:145], 0, s[64:65]
	s_add_i32 m0, s27, 0xe000
	s_nop 0
	global_load_lds_dwordx4 v[144:145], off
	s_waitcnt vmcnt(8)
	s_waitcnt lgkmcnt(0)
	s_barrier
	s_waitcnt lgkmcnt(0)
	v_mfma_f32_16x16x32_bf16 v[126:129], v[132:135], v[196:199], 0
	v_mfma_f32_16x16x32_bf16 v[122:125], v[140:143], v[196:199], 0
	v_mfma_f32_16x16x32_bf16 v[118:121], v[132:135], v[204:207], 0
	v_mfma_f32_16x16x32_bf16 v[114:117], v[140:143], v[204:207], 0
	v_mfma_f32_16x16x32_bf16 v[106:109], v[132:135], v[214:217], 0
	v_mfma_f32_16x16x32_bf16 v[98:101], v[140:143], v[214:217], 0
	v_mfma_f32_16x16x32_bf16 v[94:97], v[132:135], v[222:225], 0
	v_mfma_f32_16x16x32_bf16 v[86:89], v[140:143], v[222:225], 0
	v_mfma_f32_16x16x32_bf16 v[126:129], v[136:139], v[200:203], v[126:129]
	v_mfma_f32_16x16x32_bf16 v[122:125], v[176:179], v[200:203], v[122:125]
	v_mfma_f32_16x16x32_bf16 v[118:121], v[136:139], v[210:213], v[118:121]
	v_mfma_f32_16x16x32_bf16 v[114:117], v[176:179], v[210:213], v[114:117]
	v_mfma_f32_16x16x32_bf16 v[106:109], v[136:139], v[218:221], v[106:109]
	v_mfma_f32_16x16x32_bf16 v[98:101], v[176:179], v[218:221], v[98:101]
	v_mfma_f32_16x16x32_bf16 v[94:97], v[136:139], v[226:229], v[94:97]
	v_mfma_f32_16x16x32_bf16 v[86:89], v[176:179], v[226:229], v[86:89]
	v_mfma_f32_16x16x32_bf16 v[110:113], v[180:183], v[196:199], 0
	v_mfma_f32_16x16x32_bf16 v[102:105], v[188:191], v[196:199], 0
	v_mfma_f32_16x16x32_bf16 v[90:93], v[180:183], v[204:207], 0
	v_mfma_f32_16x16x32_bf16 v[82:85], v[188:191], v[204:207], 0
	v_mfma_f32_16x16x32_bf16 v[78:81], v[180:183], v[214:217], 0
	v_mfma_f32_16x16x32_bf16 v[74:77], v[188:191], v[214:217], 0
	v_mfma_f32_16x16x32_bf16 v[70:73], v[180:183], v[222:225], 0
	v_mfma_f32_16x16x32_bf16 v[66:69], v[188:191], v[222:225], 0
	v_mfma_f32_16x16x32_bf16 v[110:113], v[184:187], v[200:203], v[110:113]
	v_mfma_f32_16x16x32_bf16 v[102:105], v[192:195], v[200:203], v[102:105]
	v_mfma_f32_16x16x32_bf16 v[90:93], v[184:187], v[210:213], v[90:93]
	v_mfma_f32_16x16x32_bf16 v[82:85], v[192:195], v[210:213], v[82:85]
	v_mfma_f32_16x16x32_bf16 v[78:81], v[184:187], v[218:221], v[78:81]
	v_mfma_f32_16x16x32_bf16 v[74:77], v[192:195], v[218:221], v[74:77]
	v_mfma_f32_16x16x32_bf16 v[70:73], v[184:187], v[226:229], v[70:73]
	v_mfma_f32_16x16x32_bf16 v[66:69], v[192:195], v[226:229], v[66:69]
	s_barrier
	v_lshl_add_u64 v[144:145], s[30:31], 0, v[148:149]
	s_add_i32 s30, s52, s26
	s_mov_b32 m0, s30
	ds_read_b128 v[196:199], v175 offset:16384
	ds_read_b128 v[200:203], v175 offset:17408
	ds_read_b128 v[204:207], v175 offset:18432
	ds_read_b128 v[210:213], v175 offset:19456
	ds_read_b128 v[214:217], v175 offset:20480
	ds_read_b128 v[218:221], v175 offset:21504
	ds_read_b128 v[222:225], v175 offset:22528
	ds_read_b128 v[226:229], v175 offset:23552
	global_load_lds_dwordx4 v[144:145], off
	v_lshl_add_u64 v[230:231], v[144:145], 0, s[10:11]
	s_add_i32 m0, s30, 0x2000
	s_add_i32 s30, s53, s26
	global_load_lds_dwordx4 v[230:231], off
	v_lshl_add_u64 v[230:231], v[144:145], 0, s[12:13]
	s_mov_b32 m0, s30
	s_nop 0
	global_load_lds_dwordx4 v[230:231], off
	v_lshl_add_u64 v[230:231], v[144:145], 0, s[14:15]
	s_add_i32 m0, s30, 0x2000
	s_nop 0
	global_load_lds_dwordx4 v[230:231], off
	v_lshl_add_u64 v[230:231], s[28:29], 0, v[150:151]
	s_mov_b32 m0, s27
	v_lshl_add_u64 v[232:233], v[230:231], 0, s[10:11]
	global_load_lds_dwordx4 v[230:231], off
	s_mov_b32 m0, s33
	s_nop 0
	global_load_lds_dwordx4 v[232:233], off
	s_waitcnt vmcnt(8)
	s_waitcnt lgkmcnt(0)
	s_barrier
	s_waitcnt lgkmcnt(0)
	v_mfma_f32_16x16x32_bf16 v[62:65], v[132:135], v[196:199], 0
	v_mfma_f32_16x16x32_bf16 v[58:61], v[140:143], v[196:199], 0
	v_mfma_f32_16x16x32_bf16 v[54:57], v[132:135], v[204:207], 0
	v_mfma_f32_16x16x32_bf16 v[50:53], v[140:143], v[204:207], 0
	v_mfma_f32_16x16x32_bf16 v[46:49], v[132:135], v[214:217], 0
	v_mfma_f32_16x16x32_bf16 v[38:41], v[140:143], v[214:217], 0
	v_mfma_f32_16x16x32_bf16 v[30:33], v[132:135], v[222:225], 0
	v_mfma_f32_16x16x32_bf16 v[22:25], v[140:143], v[222:225], 0
	v_mfma_f32_16x16x32_bf16 v[62:65], v[136:139], v[200:203], v[62:65]
	v_mfma_f32_16x16x32_bf16 v[58:61], v[176:179], v[200:203], v[58:61]
	v_mfma_f32_16x16x32_bf16 v[54:57], v[136:139], v[210:213], v[54:57]
	v_mfma_f32_16x16x32_bf16 v[50:53], v[176:179], v[210:213], v[50:53]
	v_mfma_f32_16x16x32_bf16 v[46:49], v[136:139], v[218:221], v[46:49]
	v_mfma_f32_16x16x32_bf16 v[38:41], v[176:179], v[218:221], v[38:41]
	v_mfma_f32_16x16x32_bf16 v[30:33], v[136:139], v[226:229], v[30:33]
	v_mfma_f32_16x16x32_bf16 v[22:25], v[176:179], v[226:229], v[22:25]
	v_mfma_f32_16x16x32_bf16 v[42:45], v[180:183], v[196:199], 0
	v_mfma_f32_16x16x32_bf16 v[34:37], v[188:191], v[196:199], 0
	v_mfma_f32_16x16x32_bf16 v[26:29], v[180:183], v[204:207], 0
	v_mfma_f32_16x16x32_bf16 v[18:21], v[188:191], v[204:207], 0
	v_mfma_f32_16x16x32_bf16 v[14:17], v[180:183], v[214:217], 0
	v_mfma_f32_16x16x32_bf16 v[10:13], v[188:191], v[214:217], 0
	v_mfma_f32_16x16x32_bf16 v[6:9], v[180:183], v[222:225], 0
	v_mfma_f32_16x16x32_bf16 v[2:5], v[188:191], v[222:225], 0
	v_mfma_f32_16x16x32_bf16 v[42:45], v[184:187], v[200:203], v[42:45]
	v_mfma_f32_16x16x32_bf16 v[34:37], v[192:195], v[200:203], v[34:37]
	v_mfma_f32_16x16x32_bf16 v[26:29], v[184:187], v[210:213], v[26:29]
	v_mfma_f32_16x16x32_bf16 v[18:21], v[192:195], v[210:213], v[18:21]
	v_mfma_f32_16x16x32_bf16 v[14:17], v[184:187], v[218:221], v[14:17]
	v_mfma_f32_16x16x32_bf16 v[10:13], v[192:195], v[218:221], v[10:13]
	v_mfma_f32_16x16x32_bf16 v[6:9], v[184:187], v[226:229], v[6:9]
	v_mfma_f32_16x16x32_bf16 v[2:5], v[192:195], v[226:229], v[2:5]
	s_branch .Lmid_277

; #define G8_STA(bufoff, ptr, sg, h) G8_STAGE1(bufoff, (ptr) + (h) * ((sg) ? hA1 : hA0), ((sg) ? voffA1 : voffA0), ((sg) ? r64A1 : r64A0))
; #define G8_STB(bufoff, ptr, sg, h) G8_STAGE1(bufoff, (ptr) + (h) * ((sg) ? hB1 : hB0), ((sg) ? voffB1 : voffB0), ((sg) ? r64B1 : r64B0))
; #define G8_LDA(dst, b, h) do { _Pragma("unroll") for (int m = 0; m < 4; ++m) _Pragma("unroll") for (int k = 0; k < 2; ++k) dst[m][k] = *(const LAS bf16x8*)(lds + G8_SA(b, h) + aoff + m * 2048 + k * 1024); } while (0)
; #define G8_LDB(dst, b, h) do { _Pragma("unroll") for (int n = 0; n < 2; ++n) _Pragma("unroll") for (int k = 0; k < 2; ++k) dst[n][k] = *(const LAS bf16x8*)(lds + G8_SB(b, h) + boff + n * 2048 + k * 1024); } while (0)
; #define G8_MMA(ai, bj, At, Bt) do { __builtin_amdgcn_s_setprio(1); _Pragma("unroll") for (int m = 0; m < 4; ++m) _Pragma("unroll") for (int n = 0; n < 2; ++n) _Pragma("unroll") for (int k = 0; k < 2; ++k) \
;         acc[ai][bj][m][n] = __builtin_amdgcn_mfma_f32_16x16x32_bf16(Bt[n][k], At[m][k], acc[ai][bj][m][n], 0, 0, 0); __builtin_amdgcn_s_setprio(0); } while (0)
; #define G8_WAIT_V(n) asm volatile("s_waitcnt vmcnt(" #n ")" ::: "memory")
; #define G8_WAIT_L(n) asm volatile("s_waitcnt lgkmcnt(" #n ")" ::: "memory")
; #define G8_BAR __builtin_amdgcn_s_barrier()
; #define G8_SCHED __builtin_amdgcn_sched_barrier(0)
; template <class P>
; __device__ __forceinline__ void gemm_phase(LAS unsigned char* lds, const P& p, const int G, const int c) {
;     ...
;             G8_LDB(B0, 1, 0); G8_LDB(B1, 1, 1); G8_SCHED; G8_LDA(At, 1, 0); G8_STA(G8_SA(0, 1), a2, sg2, 1);
;             G8_WAIT_V(8); G8_WAIT_L(0); G8_BAR; G8_MMA(0, 0, At, B0); G8_MMA(0, 1, At, B1); G8_BAR; G8_SCHED;
;             G8_LDA(At, 1, 1); G8_STB(G8_SB(1, 0), b3, sg2, 0); G8_STB(G8_SB(1, 1), b3, sg2, 1); G8_STA(G8_SA(1, 0), a3, sg2, 0);
;             G8_WAIT_V(8); G8_WAIT_L(0); G8_BAR; G8_MMA(1, 0, At, B0); G8_MMA(1, 1, At, B1); G8_BAR; G8_SCHED;
;         }
.Lmid_277:
	s_barrier
	s_add_i32 s28, 0, 0x18000
	s_add_i32 s29, 0, 0x1c000
	v_add_u32_e32 v176, s28, v1
	v_add_u32_e32 v192, s29, v1
	ds_read_b128 v[132:135], v176
	ds_read_b128 v[136:139], v176 offset:1024
	ds_read_b128 v[140:143], v176 offset:2048
	ds_read_b128 v[176:179], v176 offset:3072
	ds_read_b128 v[180:183], v192
	ds_read_b128 v[184:187], v192 offset:1024
	ds_read_b128 v[188:191], v192 offset:2048
	ds_read_b128 v[192:195], v192 offset:3072
	s_mov_b32 m0, s34
	v_lshl_add_u64 v[232:233], v[230:231], 0, s[12:13]
	ds_read_b128 v[196:199], v175 offset:32768
	ds_read_b128 v[200:203], v175 offset:33792
	ds_read_b128 v[204:207], v175 offset:34816
	ds_read_b128 v[210:213], v175 offset:35840
	ds_read_b128 v[214:217], v175 offset:36864
	ds_read_b128 v[218:221], v175 offset:37888
	ds_read_b128 v[222:225], v175 offset:38912
	ds_read_b128 v[226:229], v175 offset:39936
	global_load_lds_dwordx4 v[232:233], off
	v_lshl_add_u64 v[232:233], v[230:231], 0, s[14:15]
	s_mov_b32 m0, s35
	s_nop 0
	global_load_lds_dwordx4 v[232:233], off
	s_waitcnt vmcnt(8)
	s_waitcnt lgkmcnt(0)
	s_barrier
	s_waitcnt lgkmcnt(0)
	v_mfma_f32_16x16x32_bf16 v[126:129], v[132:135], v[196:199], v[126:129]
	v_mfma_f32_16x16x32_bf16 v[122:125], v[140:143], v[196:199], v[122:125]
	v_mfma_f32_16x16x32_bf16 v[118:121], v[132:135], v[204:207], v[118:121]
	v_mfma_f32_16x16x32_bf16 v[114:117], v[140:143], v[204:207], v[114:117]
	v_mfma_f32_16x16x32_bf16 v[106:109], v[132:135], v[214:217], v[106:109]
	v_mfma_f32_16x16x32_bf16 v[98:101], v[140:143], v[214:217], v[98:101]
	v_mfma_f32_16x16x32_bf16 v[94:97], v[132:135], v[222:225], v[94:97]
	v_mfma_f32_16x16x32_bf16 v[86:89], v[140:143], v[222:225], v[86:89]
	v_mfma_f32_16x16x32_bf16 v[126:129], v[136:139], v[200:203], v[126:129]
	v_mfma_f32_16x16x32_bf16 v[122:125], v[176:179], v[200:203], v[122:125]
	v_mfma_f32_16x16x32_bf16 v[118:121], v[136:139], v[210:213], v[118:121]
	v_mfma_f32_16x16x32_bf16 v[114:117], v[176:179], v[210:213], v[114:117]
	v_mfma_f32_16x16x32_bf16 v[106:109], v[136:139], v[218:221], v[106:109]
	v_mfma_f32_16x16x32_bf16 v[98:101], v[176:179], v[218:221], v[98:101]
	v_mfma_f32_16x16x32_bf16 v[94:97], v[136:139], v[226:229], v[94:97]
	v_mfma_f32_16x16x32_bf16 v[86:89], v[176:179], v[226:229], v[86:89]
	v_mfma_f32_16x16x32_bf16 v[110:113], v[180:183], v[196:199], v[110:113]
	v_mfma_f32_16x16x32_bf16 v[102:105], v[188:191], v[196:199], v[102:105]
	v_mfma_f32_16x16x32_bf16 v[90:93], v[180:183], v[204:207], v[90:93]
	v_mfma_f32_16x16x32_bf16 v[82:85], v[188:191], v[204:207], v[82:85]
	v_mfma_f32_16x16x32_bf16 v[78:81], v[180:183], v[214:217], v[78:81]
	v_mfma_f32_16x16x32_bf16 v[74:77], v[188:191], v[214:217], v[74:77]
	v_mfma_f32_16x16x32_bf16 v[70:73], v[180:183], v[222:225], v[70:73]
	v_mfma_f32_16x16x32_bf16 v[66:69], v[188:191], v[222:225], v[66:69]
	v_mfma_f32_16x16x32_bf16 v[110:113], v[184:187], v[200:203], v[110:113]
	v_mfma_f32_16x16x32_bf16 v[102:105], v[192:195], v[200:203], v[102:105]
	v_mfma_f32_16x16x32_bf16 v[90:93], v[184:187], v[210:213], v[90:93]
	v_mfma_f32_16x16x32_bf16 v[82:85], v[192:195], v[210:213], v[82:85]
	v_mfma_f32_16x16x32_bf16 v[78:81], v[184:187], v[218:221], v[78:81]
	v_mfma_f32_16x16x32_bf16 v[74:77], v[192:195], v[218:221], v[74:77]
	v_mfma_f32_16x16x32_bf16 v[70:73], v[184:187], v[226:229], v[70:73]
	v_mfma_f32_16x16x32_bf16 v[66:69], v[192:195], v[226:229], v[66:69]
	s_barrier
	s_add_i32 s28, s28, s26
	v_lshl_add_u64 v[232:233], v[144:145], 0, s[20:21]
	s_mov_b32 m0, s28
	ds_read_b128 v[196:199], v175 offset:49152
	ds_read_b128 v[200:203], v175 offset:50176
	ds_read_b128 v[204:207], v175 offset:51200
	ds_read_b128 v[210:213], v175 offset:52224
	ds_read_b128 v[214:217], v175 offset:53248
	ds_read_b128 v[218:221], v175 offset:54272
	ds_read_b128 v[222:225], v175 offset:55296
	ds_read_b128 v[226:229], v175 offset:56320
	global_load_lds_dwordx4 v[232:233], off
	v_lshl_add_u64 v[232:233], v[144:145], 0, s[22:23]
	s_add_i32 m0, s28, 0x2000
	s_add_i32 s28, s29, s26
	global_load_lds_dwordx4 v[232:233], off
	v_lshl_add_u64 v[232:233], v[144:145], 0, s[40:41]
	s_mov_b32 m0, s28
	v_lshl_add_u64 v[144:145], v[144:145], 0, s[42:43]
	global_load_lds_dwordx4 v[232:233], off
	s_add_i32 m0, s28, 0x2000
	s_nop 0
	global_load_lds_dwordx4 v[144:145], off
	v_lshl_add_u64 v[144:145], v[230:231], 0, s[36:37]
	s_mov_b32 m0, s50
	s_nop 0
	global_load_lds_dwordx4 v[144:145], off
	v_lshl_add_u64 v[144:145], v[230:231], 0, s[38:39]
	s_mov_b32 m0, s51
	s_nop 0
	global_load_lds_dwordx4 v[144:145], off
	s_waitcnt vmcnt(8)
	s_waitcnt lgkmcnt(0)
	s_barrier
	s_waitcnt lgkmcnt(0)
	v_mfma_f32_16x16x32_bf16 v[62:65], v[132:135], v[196:199], v[62:65]
	v_mfma_f32_16x16x32_bf16 v[58:61], v[140:143], v[196:199], v[58:61]
	v_mfma_f32_16x16x32_bf16 v[54:57], v[132:135], v[204:207], v[54:57]
	v_mfma_f32_16x16x32_bf16 v[50:53], v[140:143], v[204:207], v[50:53]
	v_mfma_f32_16x16x32_bf16 v[46:49], v[132:135], v[214:217], v[46:49]
	v_mfma_f32_16x16x32_bf16 v[38:41], v[140:143], v[214:217], v[38:41]
	v_mfma_f32_16x16x32_bf16 v[30:33], v[132:135], v[222:225], v[30:33]
	v_mfma_f32_16x16x32_bf16 v[22:25], v[140:143], v[222:225], v[22:25]
	v_mfma_f32_16x16x32_bf16 v[62:65], v[136:139], v[200:203], v[62:65]
	v_mfma_f32_16x16x32_bf16 v[58:61], v[176:179], v[200:203], v[58:61]
	v_mfma_f32_16x16x32_bf16 v[54:57], v[136:139], v[210:213], v[54:57]
	v_mfma_f32_16x16x32_bf16 v[50:53], v[176:179], v[210:213], v[50:53]
	v_mfma_f32_16x16x32_bf16 v[46:49], v[136:139], v[218:221], v[46:49]
	v_mfma_f32_16x16x32_bf16 v[38:41], v[176:179], v[218:221], v[38:41]
	v_mfma_f32_16x16x32_bf16 v[30:33], v[136:139], v[226:229], v[30:33]
	v_mfma_f32_16x16x32_bf16 v[22:25], v[176:179], v[226:229], v[22:25]
	v_mfma_f32_16x16x32_bf16 v[42:45], v[180:183], v[196:199], v[42:45]
	v_mfma_f32_16x16x32_bf16 v[34:37], v[188:191], v[196:199], v[34:37]
	v_mfma_f32_16x16x32_bf16 v[26:29], v[180:183], v[204:207], v[26:29]
	v_mfma_f32_16x16x32_bf16 v[18:21], v[188:191], v[204:207], v[18:21]
	v_mfma_f32_16x16x32_bf16 v[14:17], v[180:183], v[214:217], v[14:17]
	v_mfma_f32_16x16x32_bf16 v[10:13], v[188:191], v[214:217], v[10:13]
	v_mfma_f32_16x16x32_bf16 v[6:9], v[180:183], v[222:225], v[6:9]
	v_mfma_f32_16x16x32_bf16 v[2:5], v[188:191], v[222:225], v[2:5]
	v_mfma_f32_16x16x32_bf16 v[42:45], v[184:187], v[200:203], v[42:45]
	v_mfma_f32_16x16x32_bf16 v[34:37], v[192:195], v[200:203], v[34:37]
	v_mfma_f32_16x16x32_bf16 v[26:29], v[184:187], v[210:213], v[26:29]
	v_mfma_f32_16x16x32_bf16 v[18:21], v[192:195], v[210:213], v[18:21]
	v_mfma_f32_16x16x32_bf16 v[14:17], v[184:187], v[218:221], v[14:17]
	v_mfma_f32_16x16x32_bf16 v[10:13], v[192:195], v[218:221], v[10:13]
	v_mfma_f32_16x16x32_bf16 v[6:9], v[184:187], v[226:229], v[6:9]
	v_mfma_f32_16x16x32_bf16 v[2:5], v[192:195], v[226:229], v[2:5]
	s_barrier
	s_add_u32 s19, s19, 0x40000
	s_addc_u32 s49, s49, 0
	s_add_u32 s76, s76, 0x820000
	s_addc_u32 s77, s77, 0
	s_cmp_ge_u32 s57, s5
	s_cbranch_scc1 .LBB0_282

;     __host__ __device__ bool unit(int L, Unit& u) const { return order_mn(L, RT / 256, 32, u); }
;     __host__ __device__ const char* a_base(const Unit& u, int) const { return ((u.pn < 16 || u.pm >= 128) ? HX : HXV) + (size_t)u.pm * 256 * 128; }
;     __host__ __device__ bool unit(int L, Unit& u) const { if (L >= NCHB / 256) return false; u.g = g; u.pm = 0; u.pn = b * (NCHB / 256) + L; u.ks = 0; return true; }
;     __host__ __device__ bool unit(int L, Unit& u) const { constexpr int nN = TP / 256, nM = NCHB / 256; if (L >= nN * nM) return false; u.g = g; u.pm = b * nM + L / nN; u.pn = L % nN; u.ks = 0; return true; }
;     __host__ __device__ bool unit(int L, Unit& u) const { return order_mn(L, RL / 256, 8, u); }
;     __host__ __device__ bool unit(int L, Unit& u) const { return order_mn(L, RL / 256, 4, u); }
; template <class P>
; __device__ __forceinline__ void gemm_phase(LAS unsigned char* lds, const P& p, const int G, const int c) {
;     ...
;         const bool has_next = p.unit((ui + 1) * G + c, nxt);
;         const int nt = p.nt(cur);
;         const char* nA0 = has_next ? p.a_base(nxt, 0) - p.a_bias(0) : cA0; const char* nA1 = has_next ? p.a_base(nxt, S1) - p.a_bias(S1) : cA1;
;         const char* nB0 = has_next ? p.b_base(nxt, 0) - p.b_bias(0) : cB0; const char* nB1 = has_next ? p.b_base(nxt, S1) - p.b_bias(S1) : cB1;
;         for (int t = 0; t < nt; t += 2) {
;             const bool last = (t == nt - 2);
;             const bool sg1 = (NS > 1) && (t + 1 >= nt0);
;             const bool sg2 = (NS > 1) && !last && (t + 2 >= nt0);
;             const char* a1 = sg1 ? cA1 + (long)(t + 1 - nt0) * ksA1 : cA0 + (long)(t + 1) * ksA0;
;             const char* a2 = last ? nA0 : (sg2 ? cA1 + (long)(t + 2 - nt0) * ksA1 : cA0 + (long)(t + 2) * ksA0);
;             const char* b2 = last ? nB0 : (sg2 ? cB1 + (long)(t + 2 - nt0) * ksB1 : cB0 + (long)(t + 2) * ksB0);
.LBB0_409:
	s_cmpk_lt_i32 s0, 0x80
	s_cselect_b64 s[68:69], -1, 0
	s_cmpk_gt_i32 s0, 0x7f
	s_cselect_b32 s1, 4, 16
	s_lshl_b32 s18, s72, 8
	s_ashr_i32 s19, s18, 31
	s_lshl_b64 s[18:19], s[18:19], 7
	s_lshl_b64 s[28:29], s[52:53], 21
	s_add_u32 s7, s24, s18
	s_addc_u32 s18, s25, s19
	s_add_u32 s60, s7, s28
	s_addc_u32 s61, s18, s29
	s_and_b64 s[18:19], exec, s[56:57]
	s_cselect_b32 s7, s61, s71
	s_cselect_b32 s18, s60, s70
	s_add_u32 s19, s70, 0x100000
	s_mul_i32 s28, s1, 0x410000
	s_addc_u32 s53, s71, 0
	v_lshl_add_u64 v[140:141], s[62:63], 0, v[138:139]
	s_add_i32 s55, s28, 0xff7e0000
	s_mov_b32 s74, 0
	s_mov_b64 s[70:71], 0
	s_cmp_eq_u32 s55, s70
	s_cselect_b64 s[30:31], -1, 0
	s_and_b64 vcc, exec, s[30:31]
	s_mov_b64 s[28:29], s[58:59]
	s_cbranch_vccnz .Lpeel_410
	s_add_u32 s28, s62, s70
	s_addc_u32 s29, s63, s71
	s_add_u32 s28, s28, 0x820000
	s_addc_u32 s29, s29, 0
; #define G8_STA(bufoff, ptr, sg, h) G8_STAGE1(bufoff, (ptr) + (h) * ((sg) ? hA1 : hA0), ((sg) ? voffA1 : voffA0), ((sg) ? r64A1 : r64A0))
; #define G8_STB(bufoff, ptr, sg, h) G8_STAGE1(bufoff, (ptr) + (h) * ((sg) ? hB1 : hB0), ((sg) ? voffB1 : voffB0), ((sg) ? r64B1 : r64B0))
; #define G8_LDA(dst, b, h) do { _Pragma("unroll") for (int m = 0; m < 4; ++m) _Pragma("unroll") for (int k = 0; k < 2; ++k) dst[m][k] = *(const LAS bf16x8*)(lds + G8_SA(b, h) + aoff + m * 2048 + k * 1024); } while (0)
; #define G8_LDB(dst, b, h) do { _Pragma("unroll") for (int n = 0; n < 2; ++n) _Pragma("unroll") for (int k = 0; k < 2; ++k) dst[n][k] = *(const LAS bf16x8*)(lds + G8_SB(b, h) + boff + n * 2048 + k * 1024); } while (0)
; #define G8_MMA(ai, bj, At, Bt) do { __builtin_amdgcn_s_setprio(1); _Pragma("unroll") for (int m = 0; m < 4; ++m) _Pragma("unroll") for (int n = 0; n < 2; ++n) _Pragma("unroll") for (int k = 0; k < 2; ++k) \
;         acc[ai][bj][m][n] = __builtin_amdgcn_mfma_f32_16x16x32_bf16(Bt[n][k], At[m][k], acc[ai][bj][m][n], 0, 0, 0); __builtin_amdgcn_s_setprio(0); } while (0)
; #define G8_WAIT_V(n) asm volatile("s_waitcnt vmcnt(" #n ")" ::: "memory")
; #define G8_WAIT_L(n) asm volatile("s_waitcnt lgkmcnt(" #n ")" ::: "memory")
; #define G8_BAR __builtin_amdgcn_s_barrier()
; #define G8_SCHED __builtin_amdgcn_sched_barrier(0)
; template <class P>
; __device__ __forceinline__ void gemm_phase(LAS unsigned char* lds, const P& p, const int G, const int c) {
;     ...
;             G8_LDB(B0, 0, 0); G8_LDB(B1, 0, 1); G8_SCHED; G8_LDA(At, 0, 0); G8_STA(G8_SA(1, 1), a1, sg1, 1);
;             G8_WAIT_V(8); G8_WAIT_L(0); G8_BAR; G8_MMA(0, 0, At, B0); G8_MMA(0, 1, At, B1); G8_BAR; G8_SCHED;
;             G8_LDA(At, 0, 1); G8_STB(G8_SB(0, 0), b2, sg2, 0); G8_STB(G8_SB(0, 1), b2, sg2, 1); G8_STA(G8_SA(0, 0), a2, sg2, 0);
;             G8_WAIT_V(8); G8_WAIT_L(0); G8_BAR; G8_MMA(1, 0, At, B0); G8_MMA(1, 1, At, B1); G8_BAR; G8_SCHED;
.Lpeel_410:
	v_add_u32_e32 v130, s65, v137
	ds_read_b128 v[142:145], v130
	ds_read_b128 v[146:149], v130 offset:1024
	ds_read_b128 v[162:165], v130 offset:2048
	ds_read_b128 v[166:169], v130 offset:3072
	v_add_u32_e32 v130, s66, v137
	ds_read_b128 v[170:173], v130
	ds_read_b128 v[174:177], v130 offset:1024
	ds_read_b128 v[178:181], v130 offset:2048
	ds_read_b128 v[182:185], v130 offset:3072
	s_add_i32 s74, s74, 2
	s_and_b64 s[30:31], exec, s[30:31]
	s_cselect_b32 s31, s7, s53
	s_cselect_b32 s30, s18, s19
	v_lshl_add_u64 v[206:207], v[140:141], 0, s[70:71]
	v_lshl_add_u64 v[222:223], v[206:207], 0, s[76:77]
	s_add_i32 m0, s27, 0xc000
	ds_read_b128 v[186:189], v158
	ds_read_b128 v[190:193], v158 offset:1024
	ds_read_b128 v[194:197], v158 offset:2048
	ds_read_b128 v[198:201], v158 offset:3072
	ds_read_b128 v[202:205], v158 offset:4096
	ds_read_b128 v[210:213], v158 offset:5120
	ds_read_b128 v[214:217], v158 offset:6144
	ds_read_b128 v[218:221], v158 offset:7168
	global_load_lds_dwordx4 v[222:223], off
	v_lshl_add_u64 v[206:207], v[206:207], 0, s[48:49]
	s_add_i32 m0, s27, 0xe000
	s_nop 0
	global_load_lds_dwordx4 v[206:207], off
	s_waitcnt vmcnt(8)
	s_waitcnt lgkmcnt(0)
	s_barrier
	s_waitcnt lgkmcnt(0)
	v_mfma_f32_16x16x32_bf16 v[126:129], v[142:145], v[186:189], 0
	v_mfma_f32_16x16x32_bf16 v[122:125], v[162:165], v[186:189], 0
	v_mfma_f32_16x16x32_bf16 v[110:113], v[142:145], v[194:197], 0
	v_mfma_f32_16x16x32_bf16 v[106:109], v[162:165], v[194:197], 0
	v_mfma_f32_16x16x32_bf16 v[94:97], v[142:145], v[202:205], 0
	v_mfma_f32_16x16x32_bf16 v[90:93], v[162:165], v[202:205], 0
	v_mfma_f32_16x16x32_bf16 v[78:81], v[142:145], v[214:217], 0
	v_mfma_f32_16x16x32_bf16 v[74:77], v[162:165], v[214:217], 0
	v_mfma_f32_16x16x32_bf16 v[126:129], v[146:149], v[190:193], v[126:129]
	v_mfma_f32_16x16x32_bf16 v[122:125], v[166:169], v[190:193], v[122:125]
	v_mfma_f32_16x16x32_bf16 v[110:113], v[146:149], v[198:201], v[110:113]
	v_mfma_f32_16x16x32_bf16 v[106:109], v[166:169], v[198:201], v[106:109]
	v_mfma_f32_16x16x32_bf16 v[94:97], v[146:149], v[210:213], v[94:97]
	v_mfma_f32_16x16x32_bf16 v[90:93], v[166:169], v[210:213], v[90:93]
	v_mfma_f32_16x16x32_bf16 v[78:81], v[146:149], v[218:221], v[78:81]
	v_mfma_f32_16x16x32_bf16 v[74:77], v[166:169], v[218:221], v[74:77]
	v_mfma_f32_16x16x32_bf16 v[118:121], v[170:173], v[186:189], 0
	v_mfma_f32_16x16x32_bf16 v[114:117], v[178:181], v[186:189], 0
	v_mfma_f32_16x16x32_bf16 v[102:105], v[170:173], v[194:197], 0
	v_mfma_f32_16x16x32_bf16 v[98:101], v[178:181], v[194:197], 0
	v_mfma_f32_16x16x32_bf16 v[86:89], v[170:173], v[202:205], 0
	v_mfma_f32_16x16x32_bf16 v[82:85], v[178:181], v[202:205], 0
	v_mfma_f32_16x16x32_bf16 v[70:73], v[170:173], v[214:217], 0
	v_mfma_f32_16x16x32_bf16 v[66:69], v[178:181], v[214:217], 0
	v_mfma_f32_16x16x32_bf16 v[118:121], v[174:177], v[190:193], v[118:121]
	v_mfma_f32_16x16x32_bf16 v[114:117], v[182:185], v[190:193], v[114:117]
	v_mfma_f32_16x16x32_bf16 v[102:105], v[174:177], v[198:201], v[102:105]
	v_mfma_f32_16x16x32_bf16 v[98:101], v[182:185], v[198:201], v[98:101]
	v_mfma_f32_16x16x32_bf16 v[86:89], v[174:177], v[210:213], v[86:89]
	v_mfma_f32_16x16x32_bf16 v[82:85], v[182:185], v[210:213], v[82:85]
	v_mfma_f32_16x16x32_bf16 v[70:73], v[174:177], v[218:221], v[70:73]
	v_mfma_f32_16x16x32_bf16 v[66:69], v[182:185], v[218:221], v[66:69]
	s_barrier
	v_lshl_add_u64 v[206:207], s[30:31], 0, v[132:133]
	s_add_i32 s30, s65, s26
	s_mov_b32 m0, s30
	ds_read_b128 v[186:189], v158 offset:16384
	ds_read_b128 v[190:193], v158 offset:17408
	ds_read_b128 v[194:197], v158 offset:18432
	ds_read_b128 v[198:201], v158 offset:19456
	ds_read_b128 v[202:205], v158 offset:20480
	ds_read_b128 v[210:213], v158 offset:21504
	ds_read_b128 v[214:217], v158 offset:22528
	ds_read_b128 v[218:221], v158 offset:23552
	global_load_lds_dwordx4 v[206:207], off
	v_lshl_add_u64 v[222:223], v[206:207], 0, s[8:9]
	s_add_i32 m0, s30, 0x2000
	s_add_i32 s30, s66, s26
	global_load_lds_dwordx4 v[222:223], off
	v_lshl_add_u64 v[222:223], v[206:207], 0, s[10:11]
	s_mov_b32 m0, s30
	s_nop 0
	global_load_lds_dwordx4 v[222:223], off
	v_lshl_add_u64 v[222:223], v[206:207], 0, s[12:13]
	s_add_i32 m0, s30, 0x2000
	s_nop 0
	global_load_lds_dwordx4 v[222:223], off
	v_lshl_add_u64 v[222:223], s[28:29], 0, v[134:135]
	s_mov_b32 m0, s27
	v_lshl_add_u64 v[224:225], v[222:223], 0, s[8:9]
	global_load_lds_dwordx4 v[222:223], off
	s_mov_b32 m0, s33
	s_nop 0
	global_load_lds_dwordx4 v[224:225], off
	s_waitcnt vmcnt(8)
	s_waitcnt lgkmcnt(0)
	s_barrier
	s_waitcnt lgkmcnt(0)
	v_mfma_f32_16x16x32_bf16 v[62:65], v[142:145], v[186:189], 0
	v_mfma_f32_16x16x32_bf16 v[58:61], v[162:165], v[186:189], 0
	v_mfma_f32_16x16x32_bf16 v[46:49], v[142:145], v[194:197], 0
	v_mfma_f32_16x16x32_bf16 v[42:45], v[162:165], v[194:197], 0
	v_mfma_f32_16x16x32_bf16 v[30:33], v[142:145], v[202:205], 0
	v_mfma_f32_16x16x32_bf16 v[26:29], v[162:165], v[202:205], 0
	v_mfma_f32_16x16x32_bf16 v[14:17], v[142:145], v[214:217], 0
	v_mfma_f32_16x16x32_bf16 v[10:13], v[162:165], v[214:217], 0
	v_mfma_f32_16x16x32_bf16 v[62:65], v[146:149], v[190:193], v[62:65]
	v_mfma_f32_16x16x32_bf16 v[58:61], v[166:169], v[190:193], v[58:61]
	v_mfma_f32_16x16x32_bf16 v[46:49], v[146:149], v[198:201], v[46:49]
	v_mfma_f32_16x16x32_bf16 v[42:45], v[166:169], v[198:201], v[42:45]
	v_mfma_f32_16x16x32_bf16 v[30:33], v[146:149], v[210:213], v[30:33]
	v_mfma_f32_16x16x32_bf16 v[26:29], v[166:169], v[210:213], v[26:29]
	v_mfma_f32_16x16x32_bf16 v[14:17], v[146:149], v[218:221], v[14:17]
	v_mfma_f32_16x16x32_bf16 v[10:13], v[166:169], v[218:221], v[10:13]
	v_mfma_f32_16x16x32_bf16 v[54:57], v[170:173], v[186:189], 0
	v_mfma_f32_16x16x32_bf16 v[50:53], v[178:181], v[186:189], 0
	v_mfma_f32_16x16x32_bf16 v[38:41], v[170:173], v[194:197], 0
	v_mfma_f32_16x16x32_bf16 v[34:37], v[178:181], v[194:197], 0
	v_mfma_f32_16x16x32_bf16 v[22:25], v[170:173], v[202:205], 0
	v_mfma_f32_16x16x32_bf16 v[18:21], v[178:181], v[202:205], 0
	v_mfma_f32_16x16x32_bf16 v[6:9], v[170:173], v[214:217], 0
	v_mfma_f32_16x16x32_bf16 v[2:5], v[178:181], v[214:217], 0
	v_mfma_f32_16x16x32_bf16 v[54:57], v[174:177], v[190:193], v[54:57]
	v_mfma_f32_16x16x32_bf16 v[50:53], v[182:185], v[190:193], v[50:53]
	v_mfma_f32_16x16x32_bf16 v[38:41], v[174:177], v[198:201], v[38:41]
	v_mfma_f32_16x16x32_bf16 v[34:37], v[182:185], v[198:201], v[34:37]
	v_mfma_f32_16x16x32_bf16 v[22:25], v[174:177], v[210:213], v[22:25]
	v_mfma_f32_16x16x32_bf16 v[18:21], v[182:185], v[210:213], v[18:21]
	v_mfma_f32_16x16x32_bf16 v[6:9], v[174:177], v[218:221], v[6:9]
	v_mfma_f32_16x16x32_bf16 v[2:5], v[182:185], v[218:221], v[2:5]
	s_branch .Lmid_410

; #define G8_STA(bufoff, ptr, sg, h) G8_STAGE1(bufoff, (ptr) + (h) * ((sg) ? hA1 : hA0), ((sg) ? voffA1 : voffA0), ((sg) ? r64A1 : r64A0))
; #define G8_STB(bufoff, ptr, sg, h) G8_STAGE1(bufoff, (ptr) + (h) * ((sg) ? hB1 : hB0), ((sg) ? voffB1 : voffB0), ((sg) ? r64B1 : r64B0))
; #define G8_LDA(dst, b, h) do { _Pragma("unroll") for (int m = 0; m < 4; ++m) _Pragma("unroll") for (int k = 0; k < 2; ++k) dst[m][k] = *(const LAS bf16x8*)(lds + G8_SA(b, h) + aoff + m * 2048 + k * 1024); } while (0)
; #define G8_LDB(dst, b, h) do { _Pragma("unroll") for (int n = 0; n < 2; ++n) _Pragma("unroll") for (int k = 0; k < 2; ++k) dst[n][k] = *(const LAS bf16x8*)(lds + G8_SB(b, h) + boff + n * 2048 + k * 1024); } while (0)
; #define G8_MMA(ai, bj, At, Bt) do { __builtin_amdgcn_s_setprio(1); _Pragma("unroll") for (int m = 0; m < 4; ++m) _Pragma("unroll") for (int n = 0; n < 2; ++n) _Pragma("unroll") for (int k = 0; k < 2; ++k) \
;         acc[ai][bj][m][n] = __builtin_amdgcn_mfma_f32_16x16x32_bf16(Bt[n][k], At[m][k], acc[ai][bj][m][n], 0, 0, 0); __builtin_amdgcn_s_setprio(0); } while (0)
; #define G8_WAIT_V(n) asm volatile("s_waitcnt vmcnt(" #n ")" ::: "memory")
; #define G8_WAIT_L(n) asm volatile("s_waitcnt lgkmcnt(" #n ")" ::: "memory")
; #define G8_BAR __builtin_amdgcn_s_barrier()
; #define G8_SCHED __builtin_amdgcn_sched_barrier(0)
; template <class P>
; __device__ __forceinline__ void gemm_phase(LAS unsigned char* lds, const P& p, const int G, const int c) {
;     ...
;             G8_LDB(B0, 1, 0); G8_LDB(B1, 1, 1); G8_SCHED; G8_LDA(At, 1, 0); G8_STA(G8_SA(0, 1), a2, sg2, 1);
;             G8_WAIT_V(8); G8_WAIT_L(0); G8_BAR; G8_MMA(0, 0, At, B0); G8_MMA(0, 1, At, B1); G8_BAR; G8_SCHED;
;             G8_LDA(At, 1, 1); G8_STB(G8_SB(1, 0), b3, sg2, 0); G8_STB(G8_SB(1, 1), b3, sg2, 1); G8_STA(G8_SA(1, 0), a3, sg2, 0);
;             G8_WAIT_V(8); G8_WAIT_L(0); G8_BAR; G8_MMA(1, 0, At, B0); G8_MMA(1, 1, At, B1); G8_BAR; G8_SCHED;
;         }
.Lmid_410:
	s_barrier
	s_add_i32 s28, 0, 0x18000
	v_add_u32_e32 v130, s28, v137
	s_add_i32 s29, 0, 0x1c000
	ds_read_b128 v[142:145], v130
	ds_read_b128 v[146:149], v130 offset:1024
	ds_read_b128 v[162:165], v130 offset:2048
	ds_read_b128 v[166:169], v130 offset:3072
	v_add_u32_e32 v130, s29, v137
	ds_read_b128 v[170:173], v130
	ds_read_b128 v[174:177], v130 offset:1024
	ds_read_b128 v[178:181], v130 offset:2048
	ds_read_b128 v[182:185], v130 offset:3072
	s_mov_b32 m0, s34
	v_lshl_add_u64 v[224:225], v[222:223], 0, s[10:11]
	ds_read_b128 v[186:189], v158 offset:32768
	ds_read_b128 v[190:193], v158 offset:33792
	ds_read_b128 v[194:197], v158 offset:34816
	ds_read_b128 v[198:201], v158 offset:35840
	ds_read_b128 v[202:205], v158 offset:36864
	ds_read_b128 v[210:213], v158 offset:37888
	ds_read_b128 v[214:217], v158 offset:38912
	ds_read_b128 v[218:221], v158 offset:39936
	global_load_lds_dwordx4 v[224:225], off
	v_lshl_add_u64 v[224:225], v[222:223], 0, s[12:13]
	s_mov_b32 m0, s35
	s_nop 0
	global_load_lds_dwordx4 v[224:225], off
	s_waitcnt vmcnt(8)
	s_waitcnt lgkmcnt(0)
	s_barrier
	s_waitcnt lgkmcnt(0)
	v_mfma_f32_16x16x32_bf16 v[126:129], v[142:145], v[186:189], v[126:129]
	v_mfma_f32_16x16x32_bf16 v[122:125], v[162:165], v[186:189], v[122:125]
	v_mfma_f32_16x16x32_bf16 v[110:113], v[142:145], v[194:197], v[110:113]
	v_mfma_f32_16x16x32_bf16 v[106:109], v[162:165], v[194:197], v[106:109]
	v_mfma_f32_16x16x32_bf16 v[94:97], v[142:145], v[202:205], v[94:97]
	v_mfma_f32_16x16x32_bf16 v[90:93], v[162:165], v[202:205], v[90:93]
	v_mfma_f32_16x16x32_bf16 v[78:81], v[142:145], v[214:217], v[78:81]
	v_mfma_f32_16x16x32_bf16 v[74:77], v[162:165], v[214:217], v[74:77]
	v_mfma_f32_16x16x32_bf16 v[126:129], v[146:149], v[190:193], v[126:129]
	v_mfma_f32_16x16x32_bf16 v[122:125], v[166:169], v[190:193], v[122:125]
	v_mfma_f32_16x16x32_bf16 v[110:113], v[146:149], v[198:201], v[110:113]
	v_mfma_f32_16x16x32_bf16 v[106:109], v[166:169], v[198:201], v[106:109]
	v_mfma_f32_16x16x32_bf16 v[94:97], v[146:149], v[210:213], v[94:97]
	v_mfma_f32_16x16x32_bf16 v[90:93], v[166:169], v[210:213], v[90:93]
	v_mfma_f32_16x16x32_bf16 v[78:81], v[146:149], v[218:221], v[78:81]
	v_mfma_f32_16x16x32_bf16 v[74:77], v[166:169], v[218:221], v[74:77]
	v_mfma_f32_16x16x32_bf16 v[118:121], v[170:173], v[186:189], v[118:121]
	v_mfma_f32_16x16x32_bf16 v[114:117], v[178:181], v[186:189], v[114:117]
	v_mfma_f32_16x16x32_bf16 v[102:105], v[170:173], v[194:197], v[102:105]
	v_mfma_f32_16x16x32_bf16 v[98:101], v[178:181], v[194:197], v[98:101]
	v_mfma_f32_16x16x32_bf16 v[86:89], v[170:173], v[202:205], v[86:89]
	v_mfma_f32_16x16x32_bf16 v[82:85], v[178:181], v[202:205], v[82:85]
	v_mfma_f32_16x16x32_bf16 v[70:73], v[170:173], v[214:217], v[70:73]
	v_mfma_f32_16x16x32_bf16 v[66:69], v[178:181], v[214:217], v[66:69]
	v_mfma_f32_16x16x32_bf16 v[118:121], v[174:177], v[190:193], v[118:121]
	v_mfma_f32_16x16x32_bf16 v[114:117], v[182:185], v[190:193], v[114:117]
	v_mfma_f32_16x16x32_bf16 v[102:105], v[174:177], v[198:201], v[102:105]
	v_mfma_f32_16x16x32_bf16 v[98:101], v[182:185], v[198:201], v[98:101]
	v_mfma_f32_16x16x32_bf16 v[86:89], v[174:177], v[210:213], v[86:89]
	v_mfma_f32_16x16x32_bf16 v[82:85], v[182:185], v[210:213], v[82:85]
	v_mfma_f32_16x16x32_bf16 v[70:73], v[174:177], v[218:221], v[70:73]
	v_mfma_f32_16x16x32_bf16 v[66:69], v[182:185], v[218:221], v[66:69]
	s_barrier
	s_add_i32 s28, s28, s26
	v_lshl_add_u64 v[224:225], v[206:207], 0, s[20:21]
	s_mov_b32 m0, s28
	ds_read_b128 v[186:189], v158 offset:49152
	ds_read_b128 v[190:193], v158 offset:50176
	ds_read_b128 v[194:197], v158 offset:51200
	ds_read_b128 v[198:201], v158 offset:52224
	ds_read_b128 v[202:205], v158 offset:53248
	ds_read_b128 v[210:213], v158 offset:54272
	ds_read_b128 v[214:217], v158 offset:55296
	ds_read_b128 v[218:221], v158 offset:56320
	global_load_lds_dwordx4 v[224:225], off
	v_lshl_add_u64 v[224:225], v[206:207], 0, s[22:23]
	s_add_i32 m0, s28, 0x2000
	s_add_i32 s28, s29, s26
	global_load_lds_dwordx4 v[224:225], off
	v_lshl_add_u64 v[224:225], v[206:207], 0, s[40:41]
	s_mov_b32 m0, s28
	v_lshl_add_u64 v[206:207], v[206:207], 0, s[42:43]
	global_load_lds_dwordx4 v[224:225], off
	s_add_i32 m0, s28, 0x2000
	s_nop 0
	global_load_lds_dwordx4 v[206:207], off
	v_lshl_add_u64 v[206:207], v[222:223], 0, s[36:37]
	s_mov_b32 m0, s51
	s_nop 0
	global_load_lds_dwordx4 v[206:207], off
	v_lshl_add_u64 v[206:207], v[222:223], 0, s[38:39]
	s_mov_b32 m0, s64
	s_nop 0
	global_load_lds_dwordx4 v[206:207], off
	s_waitcnt vmcnt(8)
	s_waitcnt lgkmcnt(0)
	s_barrier
	s_waitcnt lgkmcnt(0)
	v_mfma_f32_16x16x32_bf16 v[62:65], v[142:145], v[186:189], v[62:65]
	v_mfma_f32_16x16x32_bf16 v[58:61], v[162:165], v[186:189], v[58:61]
	v_mfma_f32_16x16x32_bf16 v[46:49], v[142:145], v[194:197], v[46:49]
	v_mfma_f32_16x16x32_bf16 v[42:45], v[162:165], v[194:197], v[42:45]
	v_mfma_f32_16x16x32_bf16 v[30:33], v[142:145], v[202:205], v[30:33]
	v_mfma_f32_16x16x32_bf16 v[26:29], v[162:165], v[202:205], v[26:29]
	v_mfma_f32_16x16x32_bf16 v[14:17], v[142:145], v[214:217], v[14:17]
	v_mfma_f32_16x16x32_bf16 v[10:13], v[162:165], v[214:217], v[10:13]
	v_mfma_f32_16x16x32_bf16 v[62:65], v[146:149], v[190:193], v[62:65]
	v_mfma_f32_16x16x32_bf16 v[58:61], v[166:169], v[190:193], v[58:61]
	v_mfma_f32_16x16x32_bf16 v[46:49], v[146:149], v[198:201], v[46:49]
	v_mfma_f32_16x16x32_bf16 v[42:45], v[166:169], v[198:201], v[42:45]
	v_mfma_f32_16x16x32_bf16 v[30:33], v[146:149], v[210:213], v[30:33]
	v_mfma_f32_16x16x32_bf16 v[26:29], v[166:169], v[210:213], v[26:29]
	v_mfma_f32_16x16x32_bf16 v[14:17], v[146:149], v[218:221], v[14:17]
	v_mfma_f32_16x16x32_bf16 v[10:13], v[166:169], v[218:221], v[10:13]
	v_mfma_f32_16x16x32_bf16 v[54:57], v[170:173], v[186:189], v[54:57]
	v_mfma_f32_16x16x32_bf16 v[50:53], v[178:181], v[186:189], v[50:53]
	v_mfma_f32_16x16x32_bf16 v[38:41], v[170:173], v[194:197], v[38:41]
	v_mfma_f32_16x16x32_bf16 v[34:37], v[178:181], v[194:197], v[34:37]
	v_mfma_f32_16x16x32_bf16 v[22:25], v[170:173], v[202:205], v[22:25]
	v_mfma_f32_16x16x32_bf16 v[18:21], v[178:181], v[202:205], v[18:21]
	v_mfma_f32_16x16x32_bf16 v[6:9], v[170:173], v[214:217], v[6:9]
	v_mfma_f32_16x16x32_bf16 v[2:5], v[178:181], v[214:217], v[2:5]
	v_mfma_f32_16x16x32_bf16 v[54:57], v[174:177], v[190:193], v[54:57]
	v_mfma_f32_16x16x32_bf16 v[50:53], v[182:185], v[190:193], v[50:53]
	v_mfma_f32_16x16x32_bf16 v[38:41], v[174:177], v[198:201], v[38:41]
	v_mfma_f32_16x16x32_bf16 v[34:37], v[182:185], v[198:201], v[34:37]
	v_mfma_f32_16x16x32_bf16 v[22:25], v[174:177], v[210:213], v[22:25]
	v_mfma_f32_16x16x32_bf16 v[18:21], v[182:185], v[210:213], v[18:21]
	v_mfma_f32_16x16x32_bf16 v[6:9], v[174:177], v[218:221], v[6:9]
	v_mfma_f32_16x16x32_bf16 v[2:5], v[182:185], v[218:221], v[2:5]
	s_barrier
	s_add_u32 s19, s19, 0x100000
	s_addc_u32 s53, s53, 0
	s_add_u32 s70, s70, 0x820000
	s_addc_u32 s71, s71, 0
	s_cmp_ge_u32 s74, s1
	s_cbranch_scc1 .LBB0_415

;     __host__ __device__ bool unit(int L, Unit& u) const { return order_mn(L, RT / 256, 32, u); }
;     __host__ __device__ const char* a_base(const Unit& u, int) const { return ((u.pn < 16 || u.pm >= 128) ? HX : HXV) + (size_t)u.pm * 256 * 128; }
;     __host__ __device__ bool unit(int L, Unit& u) const { if (L >= NCHB / 256) return false; u.g = g; u.pm = 0; u.pn = b * (NCHB / 256) + L; u.ks = 0; return true; }
;     __host__ __device__ bool unit(int L, Unit& u) const { constexpr int nN = TP / 256, nM = NCHB / 256; if (L >= nN * nM) return false; u.g = g; u.pm = b * nM + L / nN; u.pn = L % nN; u.ks = 0; return true; }
;     __host__ __device__ bool unit(int L, Unit& u) const { return order_mn(L, RL / 256, 8, u); }
;     __host__ __device__ bool unit(int L, Unit& u) const { return order_mn(L, RL / 256, 4, u); }
; template <class P>
; __device__ __forceinline__ void gemm_phase(LAS unsigned char* lds, const P& p, const int G, const int c) {
;     ...
;         const bool has_next = p.unit((ui + 1) * G + c, nxt);
;         const int nt = p.nt(cur);
;         const char* nA0 = has_next ? p.a_base(nxt, 0) - p.a_bias(0) : cA0; const char* nA1 = has_next ? p.a_base(nxt, S1) - p.a_bias(S1) : cA1;
;         const char* nB0 = has_next ? p.b_base(nxt, 0) - p.b_bias(0) : cB0; const char* nB1 = has_next ? p.b_base(nxt, S1) - p.b_bias(S1) : cB1;
;         for (int t = 0; t < nt; t += 2) {
;             const bool last = (t == nt - 2);
;             const bool sg1 = (NS > 1) && (t + 1 >= nt0);
;             const bool sg2 = (NS > 1) && !last && (t + 2 >= nt0);
;             const char* a1 = sg1 ? cA1 + (long)(t + 1 - nt0) * ksA1 : cA0 + (long)(t + 1) * ksA0;
;             const char* a2 = last ? nA0 : (sg2 ? cA1 + (long)(t + 2 - nt0) * ksA1 : cA0 + (long)(t + 2) * ksA0);
;             const char* b2 = last ? nB0 : (sg2 ? cB1 + (long)(t + 2 - nt0) * ksB1 : cB0 + (long)(t + 2) * ksB0);
.LBB0_678:
	s_ashr_i32 s53, s52, 31
	s_lshl_b64 s[18:19], s[52:53], 15
	s_add_u32 s30, s2, s18
	s_addc_u32 s31, s3, s19
	s_and_b64 s[18:19], s[48:49], exec
	s_cselect_b32 s55, s31, s61
	s_cselect_b32 s54, s30, s60
	s_lshl_b32 s18, s64, 8
	s_ashr_i32 s19, s18, 31
	s_lshl_b64 s[18:19], s[18:19], 7
	s_add_u32 s18, s24, s18
	s_addc_u32 s19, s25, s19
	s_add_u32 s56, s18, 0x40000
	s_addc_u32 s57, s19, 0
	s_and_b64 s[18:19], s[48:49], exec
	s_cselect_b32 s18, s57, s29
	s_cselect_b32 s19, s56, s28
	s_add_u32 s53, s28, 0x100000
	s_addc_u32 s59, s29, 0
	v_lshl_add_u64 v[168:169], s[60:61], 0, v[166:167]
	s_mov_b32 s66, -2
	s_mov_b64 s[62:63], 0
	s_cmp_eq_u32 s62, 0x38e0000
	s_cselect_b64 s[30:31], -1, 0
	s_and_b64 vcc, exec, s[30:31]
	s_mov_b64 s[28:29], s[54:55]
	s_cbranch_vccnz .Lpeel_679
	s_add_u32 s28, s60, s62
	s_addc_u32 s29, s61, s63
	s_add_u32 s28, s28, 0x820000
	s_addc_u32 s29, s29, 0
; #define G8_STA(bufoff, ptr, sg, h) G8_STAGE1(bufoff, (ptr) + (h) * ((sg) ? hA1 : hA0), ((sg) ? voffA1 : voffA0), ((sg) ? r64A1 : r64A0))
; #define G8_STB(bufoff, ptr, sg, h) G8_STAGE1(bufoff, (ptr) + (h) * ((sg) ? hB1 : hB0), ((sg) ? voffB1 : voffB0), ((sg) ? r64B1 : r64B0))
; #define G8_LDA(dst, b, h) do { _Pragma("unroll") for (int m = 0; m < 4; ++m) _Pragma("unroll") for (int k = 0; k < 2; ++k) dst[m][k] = *(const LAS bf16x8*)(lds + G8_SA(b, h) + aoff + m * 2048 + k * 1024); } while (0)
; #define G8_LDB(dst, b, h) do { _Pragma("unroll") for (int n = 0; n < 2; ++n) _Pragma("unroll") for (int k = 0; k < 2; ++k) dst[n][k] = *(const LAS bf16x8*)(lds + G8_SB(b, h) + boff + n * 2048 + k * 1024); } while (0)
; #define G8_MMA(ai, bj, At, Bt) do { __builtin_amdgcn_s_setprio(1); _Pragma("unroll") for (int m = 0; m < 4; ++m) _Pragma("unroll") for (int n = 0; n < 2; ++n) _Pragma("unroll") for (int k = 0; k < 2; ++k) \
;         acc[ai][bj][m][n] = __builtin_amdgcn_mfma_f32_16x16x32_bf16(Bt[n][k], At[m][k], acc[ai][bj][m][n], 0, 0, 0); __builtin_amdgcn_s_setprio(0); } while (0)
; #define G8_WAIT_V(n) asm volatile("s_waitcnt vmcnt(" #n ")" ::: "memory")
; #define G8_WAIT_L(n) asm volatile("s_waitcnt lgkmcnt(" #n ")" ::: "memory")
; #define G8_BAR __builtin_amdgcn_s_barrier()
; #define G8_SCHED __builtin_amdgcn_sched_barrier(0)
; template <class P>
; __device__ __forceinline__ void gemm_phase(LAS unsigned char* lds, const P& p, const int G, const int c) {
;     ...
;             G8_LDB(B0, 0, 0); G8_LDB(B1, 0, 1); G8_SCHED; G8_LDA(At, 0, 0); G8_STA(G8_SA(1, 1), a1, sg1, 1);
;             G8_WAIT_V(8); G8_WAIT_L(0); G8_BAR; G8_MMA(0, 0, At, B0); G8_MMA(0, 1, At, B1); G8_BAR; G8_SCHED;
;             G8_LDA(At, 0, 1); G8_STB(G8_SB(0, 0), b2, sg2, 0); G8_STB(G8_SB(0, 1), b2, sg2, 1); G8_STA(G8_SA(0, 0), a2, sg2, 0);
;             G8_WAIT_V(8); G8_WAIT_L(0); G8_BAR; G8_MMA(1, 0, At, B0); G8_MMA(1, 1, At, B1); G8_BAR; G8_SCHED;
.Lpeel_679:
	v_add_u32_e32 v153, s50, v1
	ds_read_b128 v[170:173], v153
	ds_read_b128 v[174:177], v153 offset:1024
	ds_read_b128 v[178:181], v153 offset:2048
	ds_read_b128 v[182:185], v153 offset:3072
	v_add_u32_e32 v153, s51, v1
	ds_read_b128 v[186:189], v153
	ds_read_b128 v[190:193], v153 offset:1024
	ds_read_b128 v[194:197], v153 offset:2048
	ds_read_b128 v[198:201], v153 offset:3072
	s_and_b64 s[30:31], exec, s[30:31]
	s_cselect_b32 s31, s18, s59
	s_cselect_b32 s30, s19, s53
	v_lshl_add_u64 v[206:207], v[168:169], 0, s[62:63]
	v_lshl_add_u64 v[238:239], v[206:207], 0, s[40:41]
	s_add_i32 m0, s27, 0xc000
	ds_read_b128 v[202:205], v151
	ds_read_b128 v[210:213], v151 offset:1024
	ds_read_b128 v[214:217], v151 offset:2048
	ds_read_b128 v[218:221], v151 offset:3072
	ds_read_b128 v[222:225], v151 offset:4096
	ds_read_b128 v[226:229], v151 offset:5120
	ds_read_b128 v[230:233], v151 offset:6144
	ds_read_b128 v[234:237], v151 offset:7168
	global_load_lds_dwordx4 v[238:239], off
	v_lshl_add_u64 v[206:207], v[206:207], 0, s[42:43]
	s_add_i32 m0, s27, 0xe000
	s_nop 0
	global_load_lds_dwordx4 v[206:207], off
	s_waitcnt vmcnt(8)
	s_waitcnt lgkmcnt(0)
	s_barrier
	s_waitcnt lgkmcnt(0)
	v_mfma_f32_16x16x32_bf16 v[126:129], v[170:173], v[202:205], 0
	v_mfma_f32_16x16x32_bf16 v[122:125], v[178:181], v[202:205], 0
	v_mfma_f32_16x16x32_bf16 v[110:113], v[170:173], v[214:217], 0
	v_mfma_f32_16x16x32_bf16 v[106:109], v[178:181], v[214:217], 0
	v_mfma_f32_16x16x32_bf16 v[94:97], v[170:173], v[222:225], 0
	v_mfma_f32_16x16x32_bf16 v[90:93], v[178:181], v[222:225], 0
	v_mfma_f32_16x16x32_bf16 v[78:81], v[170:173], v[230:233], 0
	v_mfma_f32_16x16x32_bf16 v[74:77], v[178:181], v[230:233], 0
	v_mfma_f32_16x16x32_bf16 v[126:129], v[174:177], v[210:213], v[126:129]
	v_mfma_f32_16x16x32_bf16 v[122:125], v[182:185], v[210:213], v[122:125]
	v_mfma_f32_16x16x32_bf16 v[110:113], v[174:177], v[218:221], v[110:113]
	v_mfma_f32_16x16x32_bf16 v[106:109], v[182:185], v[218:221], v[106:109]
	v_mfma_f32_16x16x32_bf16 v[94:97], v[174:177], v[226:229], v[94:97]
	v_mfma_f32_16x16x32_bf16 v[90:93], v[182:185], v[226:229], v[90:93]
	v_mfma_f32_16x16x32_bf16 v[78:81], v[174:177], v[234:237], v[78:81]
	v_mfma_f32_16x16x32_bf16 v[74:77], v[182:185], v[234:237], v[74:77]
	v_mfma_f32_16x16x32_bf16 v[118:121], v[186:189], v[202:205], 0
	v_mfma_f32_16x16x32_bf16 v[114:117], v[194:197], v[202:205], 0
	v_mfma_f32_16x16x32_bf16 v[102:105], v[186:189], v[214:217], 0
	v_mfma_f32_16x16x32_bf16 v[98:101], v[194:197], v[214:217], 0
	v_mfma_f32_16x16x32_bf16 v[86:89], v[186:189], v[222:225], 0
	v_mfma_f32_16x16x32_bf16 v[82:85], v[194:197], v[222:225], 0
	v_mfma_f32_16x16x32_bf16 v[70:73], v[186:189], v[230:233], 0
	v_mfma_f32_16x16x32_bf16 v[66:69], v[194:197], v[230:233], 0
	v_mfma_f32_16x16x32_bf16 v[118:121], v[190:193], v[210:213], v[118:121]
	v_mfma_f32_16x16x32_bf16 v[114:117], v[198:201], v[210:213], v[114:117]
	v_mfma_f32_16x16x32_bf16 v[102:105], v[190:193], v[218:221], v[102:105]
	v_mfma_f32_16x16x32_bf16 v[98:101], v[198:201], v[218:221], v[98:101]
	v_mfma_f32_16x16x32_bf16 v[86:89], v[190:193], v[226:229], v[86:89]
	v_mfma_f32_16x16x32_bf16 v[82:85], v[198:201], v[226:229], v[82:85]
	v_mfma_f32_16x16x32_bf16 v[70:73], v[190:193], v[234:237], v[70:73]
	v_mfma_f32_16x16x32_bf16 v[66:69], v[198:201], v[234:237], v[66:69]
	s_barrier
	v_lshl_add_u64 v[206:207], s[30:31], 0, v[130:131]
	s_add_i32 s30, s50, s26
	s_mov_b32 m0, s30
	ds_read_b128 v[202:205], v151 offset:16384
	ds_read_b128 v[210:213], v151 offset:17408
	ds_read_b128 v[214:217], v151 offset:18432
	ds_read_b128 v[218:221], v151 offset:19456
	ds_read_b128 v[222:225], v151 offset:20480
	ds_read_b128 v[226:229], v151 offset:21504
	ds_read_b128 v[230:233], v151 offset:22528
	ds_read_b128 v[234:237], v151 offset:23552
	global_load_lds_dwordx4 v[206:207], off
	v_lshl_add_u64 v[238:239], v[206:207], 0, s[0:1]
	s_add_i32 m0, s30, 0x2000
	s_add_i32 s30, s51, s26
	global_load_lds_dwordx4 v[238:239], off
	v_lshl_add_u64 v[238:239], v[206:207], 0, s[4:5]
	s_mov_b32 m0, s30
	s_nop 0
	global_load_lds_dwordx4 v[238:239], off
	v_lshl_add_u64 v[238:239], v[206:207], 0, s[6:7]
	s_add_i32 m0, s30, 0x2000
	s_nop 0
	global_load_lds_dwordx4 v[238:239], off
	v_lshl_add_u64 v[238:239], s[28:29], 0, v[132:133]
	s_mov_b32 m0, s27
	v_lshl_add_u64 v[240:241], v[238:239], 0, s[0:1]
	global_load_lds_dwordx4 v[238:239], off
	s_mov_b32 m0, s33
	s_nop 0
	global_load_lds_dwordx4 v[240:241], off
	s_waitcnt vmcnt(8)
	s_waitcnt lgkmcnt(0)
	s_barrier
	s_waitcnt lgkmcnt(0)
	v_mfma_f32_16x16x32_bf16 v[62:65], v[170:173], v[202:205], 0
	v_mfma_f32_16x16x32_bf16 v[58:61], v[178:181], v[202:205], 0
	v_mfma_f32_16x16x32_bf16 v[46:49], v[170:173], v[214:217], 0
	v_mfma_f32_16x16x32_bf16 v[42:45], v[178:181], v[214:217], 0
	v_mfma_f32_16x16x32_bf16 v[30:33], v[170:173], v[222:225], 0
	v_mfma_f32_16x16x32_bf16 v[26:29], v[178:181], v[222:225], 0
	v_mfma_f32_16x16x32_bf16 v[14:17], v[170:173], v[230:233], 0
	v_mfma_f32_16x16x32_bf16 v[10:13], v[178:181], v[230:233], 0
	v_mfma_f32_16x16x32_bf16 v[62:65], v[174:177], v[210:213], v[62:65]
	v_mfma_f32_16x16x32_bf16 v[58:61], v[182:185], v[210:213], v[58:61]
	v_mfma_f32_16x16x32_bf16 v[46:49], v[174:177], v[218:221], v[46:49]
	v_mfma_f32_16x16x32_bf16 v[42:45], v[182:185], v[218:221], v[42:45]
	v_mfma_f32_16x16x32_bf16 v[30:33], v[174:177], v[226:229], v[30:33]
	v_mfma_f32_16x16x32_bf16 v[26:29], v[182:185], v[226:229], v[26:29]
	v_mfma_f32_16x16x32_bf16 v[14:17], v[174:177], v[234:237], v[14:17]
	v_mfma_f32_16x16x32_bf16 v[10:13], v[182:185], v[234:237], v[10:13]
	v_mfma_f32_16x16x32_bf16 v[54:57], v[186:189], v[202:205], 0
	v_mfma_f32_16x16x32_bf16 v[50:53], v[194:197], v[202:205], 0
	v_mfma_f32_16x16x32_bf16 v[38:41], v[186:189], v[214:217], 0
	v_mfma_f32_16x16x32_bf16 v[34:37], v[194:197], v[214:217], 0
	v_mfma_f32_16x16x32_bf16 v[22:25], v[186:189], v[222:225], 0
	v_mfma_f32_16x16x32_bf16 v[18:21], v[194:197], v[222:225], 0
	v_mfma_f32_16x16x32_bf16 v[6:9], v[186:189], v[230:233], 0
	v_mfma_f32_16x16x32_bf16 v[2:5], v[194:197], v[230:233], 0
	v_mfma_f32_16x16x32_bf16 v[54:57], v[190:193], v[210:213], v[54:57]
	v_mfma_f32_16x16x32_bf16 v[50:53], v[198:201], v[210:213], v[50:53]
	v_mfma_f32_16x16x32_bf16 v[38:41], v[190:193], v[218:221], v[38:41]
	v_mfma_f32_16x16x32_bf16 v[34:37], v[198:201], v[218:221], v[34:37]
	v_mfma_f32_16x16x32_bf16 v[22:25], v[190:193], v[226:229], v[22:25]
	v_mfma_f32_16x16x32_bf16 v[18:21], v[198:201], v[226:229], v[18:21]
	v_mfma_f32_16x16x32_bf16 v[6:9], v[190:193], v[234:237], v[6:9]
	v_mfma_f32_16x16x32_bf16 v[2:5], v[198:201], v[234:237], v[2:5]
	s_branch .Lmid_679

; #define G8_STA(bufoff, ptr, sg, h) G8_STAGE1(bufoff, (ptr) + (h) * ((sg) ? hA1 : hA0), ((sg) ? voffA1 : voffA0), ((sg) ? r64A1 : r64A0))
; #define G8_STB(bufoff, ptr, sg, h) G8_STAGE1(bufoff, (ptr) + (h) * ((sg) ? hB1 : hB0), ((sg) ? voffB1 : voffB0), ((sg) ? r64B1 : r64B0))
; #define G8_LDA(dst, b, h) do { _Pragma("unroll") for (int m = 0; m < 4; ++m) _Pragma("unroll") for (int k = 0; k < 2; ++k) dst[m][k] = *(const LAS bf16x8*)(lds + G8_SA(b, h) + aoff + m * 2048 + k * 1024); } while (0)
; #define G8_LDB(dst, b, h) do { _Pragma("unroll") for (int n = 0; n < 2; ++n) _Pragma("unroll") for (int k = 0; k < 2; ++k) dst[n][k] = *(const LAS bf16x8*)(lds + G8_SB(b, h) + boff + n * 2048 + k * 1024); } while (0)
; #define G8_MMA(ai, bj, At, Bt) do { __builtin_amdgcn_s_setprio(1); _Pragma("unroll") for (int m = 0; m < 4; ++m) _Pragma("unroll") for (int n = 0; n < 2; ++n) _Pragma("unroll") for (int k = 0; k < 2; ++k) \
;         acc[ai][bj][m][n] = __builtin_amdgcn_mfma_f32_16x16x32_bf16(Bt[n][k], At[m][k], acc[ai][bj][m][n], 0, 0, 0); __builtin_amdgcn_s_setprio(0); } while (0)
; #define G8_WAIT_V(n) asm volatile("s_waitcnt vmcnt(" #n ")" ::: "memory")
; #define G8_WAIT_L(n) asm volatile("s_waitcnt lgkmcnt(" #n ")" ::: "memory")
; #define G8_BAR __builtin_amdgcn_s_barrier()
; #define G8_SCHED __builtin_amdgcn_sched_barrier(0)
; template <class P>
; __device__ __forceinline__ void gemm_phase(LAS unsigned char* lds, const P& p, const int G, const int c) {
;     ...
;             G8_LDB(B0, 1, 0); G8_LDB(B1, 1, 1); G8_SCHED; G8_LDA(At, 1, 0); G8_STA(G8_SA(0, 1), a2, sg2, 1);
;             G8_WAIT_V(8); G8_WAIT_L(0); G8_BAR; G8_MMA(0, 0, At, B0); G8_MMA(0, 1, At, B1); G8_BAR; G8_SCHED;
;             G8_LDA(At, 1, 1); G8_STB(G8_SB(1, 0), b3, sg2, 0); G8_STB(G8_SB(1, 1), b3, sg2, 1); G8_STA(G8_SA(1, 0), a3, sg2, 0);
;             G8_WAIT_V(8); G8_WAIT_L(0); G8_BAR; G8_MMA(1, 0, At, B0); G8_MMA(1, 1, At, B1); G8_BAR; G8_SCHED;
;         }
.Lmid_679:
	s_barrier
	s_add_i32 s28, 0, 0x18000
	v_add_u32_e32 v153, s28, v1
	s_add_i32 s29, 0, 0x1c000
	ds_read_b128 v[170:173], v153
	ds_read_b128 v[174:177], v153 offset:1024
	ds_read_b128 v[178:181], v153 offset:2048
	ds_read_b128 v[182:185], v153 offset:3072
	v_add_u32_e32 v153, s29, v1
	ds_read_b128 v[186:189], v153
	ds_read_b128 v[190:193], v153 offset:1024
	ds_read_b128 v[194:197], v153 offset:2048
	ds_read_b128 v[198:201], v153 offset:3072
	s_mov_b32 m0, s34
	v_lshl_add_u64 v[240:241], v[238:239], 0, s[4:5]
	ds_read_b128 v[202:205], v151 offset:32768
	ds_read_b128 v[210:213], v151 offset:33792
	ds_read_b128 v[214:217], v151 offset:34816
	ds_read_b128 v[218:221], v151 offset:35840
	ds_read_b128 v[222:225], v151 offset:36864
	ds_read_b128 v[226:229], v151 offset:37888
	ds_read_b128 v[230:233], v151 offset:38912
	ds_read_b128 v[234:237], v151 offset:39936
	global_load_lds_dwordx4 v[240:241], off
	v_lshl_add_u64 v[240:241], v[238:239], 0, s[6:7]
	s_mov_b32 m0, s35
	s_nop 0
	global_load_lds_dwordx4 v[240:241], off
	s_waitcnt vmcnt(8)
	s_waitcnt lgkmcnt(0)
	s_barrier
	s_waitcnt lgkmcnt(0)
	v_mfma_f32_16x16x32_bf16 v[126:129], v[170:173], v[202:205], v[126:129]
	v_mfma_f32_16x16x32_bf16 v[122:125], v[178:181], v[202:205], v[122:125]
	v_mfma_f32_16x16x32_bf16 v[110:113], v[170:173], v[214:217], v[110:113]
	v_mfma_f32_16x16x32_bf16 v[106:109], v[178:181], v[214:217], v[106:109]
	v_mfma_f32_16x16x32_bf16 v[94:97], v[170:173], v[222:225], v[94:97]
	v_mfma_f32_16x16x32_bf16 v[90:93], v[178:181], v[222:225], v[90:93]
	v_mfma_f32_16x16x32_bf16 v[78:81], v[170:173], v[230:233], v[78:81]
	v_mfma_f32_16x16x32_bf16 v[74:77], v[178:181], v[230:233], v[74:77]
	v_mfma_f32_16x16x32_bf16 v[126:129], v[174:177], v[210:213], v[126:129]
	v_mfma_f32_16x16x32_bf16 v[122:125], v[182:185], v[210:213], v[122:125]
	v_mfma_f32_16x16x32_bf16 v[110:113], v[174:177], v[218:221], v[110:113]
	v_mfma_f32_16x16x32_bf16 v[106:109], v[182:185], v[218:221], v[106:109]
	v_mfma_f32_16x16x32_bf16 v[94:97], v[174:177], v[226:229], v[94:97]
	v_mfma_f32_16x16x32_bf16 v[90:93], v[182:185], v[226:229], v[90:93]
	v_mfma_f32_16x16x32_bf16 v[78:81], v[174:177], v[234:237], v[78:81]
	v_mfma_f32_16x16x32_bf16 v[74:77], v[182:185], v[234:237], v[74:77]
	v_mfma_f32_16x16x32_bf16 v[118:121], v[186:189], v[202:205], v[118:121]
	v_mfma_f32_16x16x32_bf16 v[114:117], v[194:197], v[202:205], v[114:117]
	v_mfma_f32_16x16x32_bf16 v[102:105], v[186:189], v[214:217], v[102:105]
	v_mfma_f32_16x16x32_bf16 v[98:101], v[194:197], v[214:217], v[98:101]
	v_mfma_f32_16x16x32_bf16 v[86:89], v[186:189], v[222:225], v[86:89]
	v_mfma_f32_16x16x32_bf16 v[82:85], v[194:197], v[222:225], v[82:85]
	v_mfma_f32_16x16x32_bf16 v[70:73], v[186:189], v[230:233], v[70:73]
	v_mfma_f32_16x16x32_bf16 v[66:69], v[194:197], v[230:233], v[66:69]
	v_mfma_f32_16x16x32_bf16 v[118:121], v[190:193], v[210:213], v[118:121]
	v_mfma_f32_16x16x32_bf16 v[114:117], v[198:201], v[210:213], v[114:117]
	v_mfma_f32_16x16x32_bf16 v[102:105], v[190:193], v[218:221], v[102:105]
	v_mfma_f32_16x16x32_bf16 v[98:101], v[198:201], v[218:221], v[98:101]
	v_mfma_f32_16x16x32_bf16 v[86:89], v[190:193], v[226:229], v[86:89]
	v_mfma_f32_16x16x32_bf16 v[82:85], v[198:201], v[226:229], v[82:85]
	v_mfma_f32_16x16x32_bf16 v[70:73], v[190:193], v[234:237], v[70:73]
	v_mfma_f32_16x16x32_bf16 v[66:69], v[198:201], v[234:237], v[66:69]
	s_barrier
	s_add_i32 s28, s28, s26
	v_lshl_add_u64 v[240:241], v[206:207], 0, s[12:13]
	s_mov_b32 m0, s28
	ds_read_b128 v[202:205], v151 offset:49152
	ds_read_b128 v[210:213], v151 offset:50176
	ds_read_b128 v[214:217], v151 offset:51200
	ds_read_b128 v[218:221], v151 offset:52224
	ds_read_b128 v[222:225], v151 offset:53248
	ds_read_b128 v[226:229], v151 offset:54272
	ds_read_b128 v[230:233], v151 offset:55296
	ds_read_b128 v[234:237], v151 offset:56320
	global_load_lds_dwordx4 v[240:241], off
	v_lshl_add_u64 v[240:241], v[206:207], 0, s[14:15]
	s_add_i32 m0, s28, 0x2000
	s_add_i32 s28, s29, s26
	global_load_lds_dwordx4 v[240:241], off
	v_lshl_add_u64 v[240:241], v[206:207], 0, s[22:23]
	s_mov_b32 m0, s28
	v_lshl_add_u64 v[206:207], v[206:207], 0, s[36:37]
	global_load_lds_dwordx4 v[240:241], off
	s_add_i32 m0, s28, 0x2000
	s_nop 0
	global_load_lds_dwordx4 v[206:207], off
	v_lshl_add_u64 v[206:207], v[238:239], 0, s[16:17]
	s_mov_b32 m0, s46
	s_nop 0
	global_load_lds_dwordx4 v[206:207], off
	v_lshl_add_u64 v[206:207], v[238:239], 0, s[20:21]
	s_mov_b32 m0, s47
	s_nop 0
	global_load_lds_dwordx4 v[206:207], off
	s_waitcnt vmcnt(8)
	s_waitcnt lgkmcnt(0)
	s_barrier
	s_waitcnt lgkmcnt(0)
	v_mfma_f32_16x16x32_bf16 v[62:65], v[170:173], v[202:205], v[62:65]
	v_mfma_f32_16x16x32_bf16 v[58:61], v[178:181], v[202:205], v[58:61]
	v_mfma_f32_16x16x32_bf16 v[46:49], v[170:173], v[214:217], v[46:49]
	v_mfma_f32_16x16x32_bf16 v[42:45], v[178:181], v[214:217], v[42:45]
	v_mfma_f32_16x16x32_bf16 v[30:33], v[170:173], v[222:225], v[30:33]
	v_mfma_f32_16x16x32_bf16 v[26:29], v[178:181], v[222:225], v[26:29]
	v_mfma_f32_16x16x32_bf16 v[14:17], v[170:173], v[230:233], v[14:17]
	v_mfma_f32_16x16x32_bf16 v[10:13], v[178:181], v[230:233], v[10:13]
	v_mfma_f32_16x16x32_bf16 v[62:65], v[174:177], v[210:213], v[62:65]
	v_mfma_f32_16x16x32_bf16 v[58:61], v[182:185], v[210:213], v[58:61]
	v_mfma_f32_16x16x32_bf16 v[46:49], v[174:177], v[218:221], v[46:49]
	v_mfma_f32_16x16x32_bf16 v[42:45], v[182:185], v[218:221], v[42:45]
	v_mfma_f32_16x16x32_bf16 v[30:33], v[174:177], v[226:229], v[30:33]
	v_mfma_f32_16x16x32_bf16 v[26:29], v[182:185], v[226:229], v[26:29]
	v_mfma_f32_16x16x32_bf16 v[14:17], v[174:177], v[234:237], v[14:17]
	v_mfma_f32_16x16x32_bf16 v[10:13], v[182:185], v[234:237], v[10:13]
	v_mfma_f32_16x16x32_bf16 v[54:57], v[186:189], v[202:205], v[54:57]
	v_mfma_f32_16x16x32_bf16 v[50:53], v[194:197], v[202:205], v[50:53]
	v_mfma_f32_16x16x32_bf16 v[38:41], v[186:189], v[214:217], v[38:41]
	v_mfma_f32_16x16x32_bf16 v[34:37], v[194:197], v[214:217], v[34:37]
	v_mfma_f32_16x16x32_bf16 v[22:25], v[186:189], v[222:225], v[22:25]
	v_mfma_f32_16x16x32_bf16 v[18:21], v[194:197], v[222:225], v[18:21]
	v_mfma_f32_16x16x32_bf16 v[6:9], v[186:189], v[230:233], v[6:9]
	v_mfma_f32_16x16x32_bf16 v[2:5], v[194:197], v[230:233], v[2:5]
	v_mfma_f32_16x16x32_bf16 v[54:57], v[190:193], v[210:213], v[54:57]
	v_mfma_f32_16x16x32_bf16 v[50:53], v[198:201], v[210:213], v[50:53]
	v_mfma_f32_16x16x32_bf16 v[38:41], v[190:193], v[218:221], v[38:41]
	v_mfma_f32_16x16x32_bf16 v[34:37], v[198:201], v[218:221], v[34:37]
	v_mfma_f32_16x16x32_bf16 v[22:25], v[190:193], v[226:229], v[22:25]
	v_mfma_f32_16x16x32_bf16 v[18:21], v[198:201], v[226:229], v[18:21]
	v_mfma_f32_16x16x32_bf16 v[6:9], v[190:193], v[234:237], v[6:9]
	v_mfma_f32_16x16x32_bf16 v[2:5], v[198:201], v[234:237], v[2:5]
	s_barrier
	s_add_i32 s66, s66, 2
	s_add_u32 s53, s53, 0x100000
	s_addc_u32 s59, s59, 0
	s_add_u32 s62, s62, 0x820000
	s_addc_u32 s63, s63, 0
	s_cmp_gt_u32 s66, 13
	s_cbranch_scc1 .LBB0_682
